# first-item loader version with 16 bytes of padding so that every later loop has the code alignment of the previous version
# speedup vs baseline: 1.0075x; 1.0075x over previous
.Lrl0_now12:
	s_mov_b64 exec, s[28:29]
	s_nop 0
	s_nop 0
	s_nop 0
	s_nop 0
